# fused down-GEMM tail epilogue: the 14 x1b row-group loads hoisted to the epilogue start with counted waits (was 8 serialized round trips)
# baseline (speedup 1.0000x reference)
.LBB0_1462:
	s_lshl_b32 s23, s48, 8
	v_add_u32_e32 v160, s23, v180
	s_lshr_b32 s4, s48, 4
	v_ashrrev_i32_e32 v161, 31, v160
	s_mulk_i32 s4, 0x1800
	v_lshl_or_b32 v158, s22, 8, v182
	v_lshlrev_b64 v[96:97], 11, v[160:161]
	s_ashr_i32 s5, s4, 31
	v_ashrrev_i32_e32 v159, 31, v158
	v_lshl_add_u64 v[96:97], s[74:75], 0, v[96:97]
	s_lshl_b64 s[4:5], s[4:5], 2
	v_lshl_add_u64 v[96:97], v[158:159], 1, v[96:97]
	s_add_u32 s4, s86, s4
	v_mov_b32_e32 v190, v218
	v_lshl_add_u64 v[96:97], v[96:97], 0, v[148:149]
	s_addc_u32 s5, s87, s5
	global_load_dwordx4 v[162:165], v[96:97], off
	global_load_dwordx4 v[166:169], v[96:97], off offset:256
	v_mov_b64_e32 v[226:227], v[96:97]
	v_lshl_add_u64 v[96:97], v[158:159], 2, s[4:5]
	v_add_co_u32_e32 v98, vcc, s45, v96
	v_and_b32_e32 v171, 64, v187
	s_nop 0
	v_addc_co_u32_e32 v99, vcc, 0, v97, vcc
	global_load_dwordx4 v[104:107], v[98:99], off
	v_lshl_add_u64 v[96:97], v[96:97], 0, s[16:17]
	global_load_dwordx4 v[108:111], v[96:97], off offset:64
	global_load_dwordx4 v[100:103], v[96:97], off offset:512
	s_nop 0
	global_load_dwordx4 v[96:99], v[96:97], off offset:576
	v_add_co_u32_e32 v228, vcc, 0x8000, v226
	s_nop 1
	v_addc_co_u32_e32 v229, vcc, 0, v227, vcc
	global_load_dwordx4 v[232:235], v[228:229], off offset:256
	global_load_dwordx4 v[228:231], v[228:229], off
	v_add_co_u32_e32 v236, vcc, 0x10000, v226
	s_nop 1
	v_addc_co_u32_e32 v237, vcc, 0, v227, vcc
	global_load_dwordx4 v[240:243], v[236:237], off offset:256
	global_load_dwordx4 v[236:239], v[236:237], off
	v_add_co_u32_e32 v244, vcc, 0x18000, v226
	s_nop 1
	v_addc_co_u32_e32 v245, vcc, 0, v227, vcc
	global_load_dwordx4 v[248:251], v[244:245], off offset:256
	global_load_dwordx4 v[244:247], v[244:245], off
	v_add_co_u32_e32 v252, vcc, 0x40000, v226
	s_nop 1
	v_addc_co_u32_e32 v253, vcc, 0, v227, vcc
	global_load_dwordx4 v[144:147], v[252:253], off offset:256
	global_load_dwordx4 v[252:255], v[252:253], off
	v_add_co_u32_e32 v150, vcc, 0x48000, v226
	s_nop 1
	v_addc_co_u32_e32 v151, vcc, 0, v227, vcc
	global_load_dwordx4 v[154:157], v[150:151], off offset:256
	global_load_dwordx4 v[150:153], v[150:151], off
	v_add_co_u32_e32 v210, vcc, 0x50000, v226
	s_nop 1
	v_addc_co_u32_e32 v211, vcc, 0, v227, vcc
	global_load_dwordx4 v[214:217], v[210:211], off offset:256
	global_load_dwordx4 v[210:213], v[210:211], off
	v_add_co_u32_e32 v220, vcc, 0x58000, v226
	s_nop 1
	v_addc_co_u32_e32 v221, vcc, 0, v227, vcc
	global_load_dwordx4 v[224:227], v[220:221], off offset:256
	global_load_dwordx4 v[220:223], v[220:221], off
	v_xor_b32_e32 v170, 16, v187
	v_add_u32_e32 v178, 64, v171
	v_cmp_lt_i32_e32 vcc, v170, v178
	s_waitcnt vmcnt(14)
	v_mov_b32_e32 v171, v165
	v_cndmask_b32_e32 v170, v187, v170, vcc
	v_lshlrev_b32_e32 v191, 2, v170
	v_mov_b32_e32 v170, v164
	v_mov_b32_e32 v175, v168
	v_mov_b32_e32 v177, v169
	v_permlane16_swap_b32_e32 v162, v170
	v_permlane16_swap_b32_e32 v163, v171
	v_permlane16_swap_b32_e32 v166, v175
	v_permlane16_swap_b32_e32 v167, v177
	v_lshlrev_b32_e32 v164, 16, v162
	v_and_b32_e32 v165, 0xffff0000, v162
	v_lshlrev_b32_e32 v162, 16, v163
	v_and_b32_e32 v163, 0xffff0000, v163
	v_lshlrev_b32_e32 v168, 16, v170
	v_and_b32_e32 v169, 0xffff0000, v170
	v_lshlrev_b32_e32 v170, 16, v171
	v_and_b32_e32 v171, 0xffff0000, v171
	v_lshlrev_b32_e32 v172, 16, v166
	v_and_b32_e32 v173, 0xffff0000, v166
	v_lshlrev_b32_e32 v166, 16, v167
	v_and_b32_e32 v167, 0xffff0000, v167
	v_pk_fma_f32 v[142:143], v[142:143], v[106:107], v[162:163]
	v_pk_fma_f32 v[140:141], v[140:141], v[104:105], v[164:165]
	v_pk_fma_f32 v[138:139], v[138:139], v[110:111], v[170:171]
	v_pk_fma_f32 v[136:137], v[136:137], v[108:109], v[168:169]
	v_lshlrev_b32_e32 v174, 16, v175
	v_and_b32_e32 v175, 0xffff0000, v175
	v_lshlrev_b32_e32 v176, 16, v177
	v_and_b32_e32 v177, 0xffff0000, v177
	v_pk_fma_f32 v[134:135], v[134:135], v[102:103], v[166:167]
	v_pk_fma_f32 v[132:133], v[132:133], v[100:101], v[172:173]
	v_mul_f32_e32 v162, v141, v141
	v_mul_f32_e32 v163, v143, v143
	v_mul_f32_e32 v164, v137, v137
	v_mul_f32_e32 v165, v139, v139
	v_pk_fma_f32 v[130:131], v[130:131], v[98:99], v[176:177]
	v_pk_fma_f32 v[128:129], v[128:129], v[96:97], v[174:175]
	v_mul_f32_e32 v166, v133, v133
	v_mul_f32_e32 v167, v135, v135
	v_fmac_f32_e32 v162, v140, v140
	v_fmac_f32_e32 v163, v142, v142
	v_fmac_f32_e32 v164, v136, v136
	v_fmac_f32_e32 v165, v138, v138
	v_mul_f32_e32 v168, v129, v129
	v_mul_f32_e32 v169, v131, v131
	v_fmac_f32_e32 v166, v132, v132
	v_fmac_f32_e32 v167, v134, v134
	v_add_f32_e32 v162, v162, v163
	v_add_f32_e32 v163, v164, v165
	v_fmac_f32_e32 v168, v128, v128
	v_fmac_f32_e32 v169, v130, v130
	v_add_f32_e32 v164, v166, v167
	v_add_f32_e32 v162, v162, v163
	v_add_f32_e32 v162, v162, v164
	v_add_f32_e32 v163, v168, v169
	v_add_f32_e32 v162, v163, v162
	ds_bpermute_b32 v163, v191, v162
	v_xor_b32_e32 v164, 32, v187
	v_cmp_lt_i32_e32 vcc, v164, v178
	s_waitcnt lgkmcnt(0)
	v_add_f32_e32 v162, v162, v163
	v_cndmask_b32_e32 v164, v187, v164, vcc
	v_lshlrev_b32_e32 v192, 2, v164
	ds_bpermute_b32 v163, v192, v162
	s_and_saveexec_b64 s[4:5], s[0:1]
	s_cbranch_execz .LBB0_1464
	s_waitcnt lgkmcnt(0)
	v_add_f32_e32 v162, v162, v163
	ds_write_b32 v189, v162
.LBB0_1464:
	s_or_b64 exec, exec, s[4:5]
	v_or_b32_e32 v162, 16, v160
	s_waitcnt lgkmcnt(0)
	v_ashrrev_i32_e32 v163, 31, v162
	v_lshlrev_b64 v[164:165], 11, v[162:163]
	v_lshl_add_u64 v[164:165], s[74:75], 0, v[164:165]
	v_lshl_add_u64 v[164:165], v[158:159], 1, v[164:165]
	v_lshl_add_u64 v[168:169], v[164:165], 0, v[148:149]
	s_waitcnt vmcnt(12)
	v_mov_b64_e32 v[164:165], v[228:229]
	v_mov_b64_e32 v[166:167], v[230:231]
	s_nop 0
	v_mov_b64_e32 v[168:169], v[232:233]
	v_mov_b64_e32 v[170:171], v[234:235]
	s_nop 0
	v_mov_b32_e32 v172, v166
	v_mov_b32_e32 v173, v167
	s_nop 0
	v_mov_b32_e32 v177, v170
	v_mov_b32_e32 v179, v171
	v_permlane16_swap_b32_e32 v164, v172
	v_permlane16_swap_b32_e32 v165, v173
	v_permlane16_swap_b32_e32 v168, v177
	v_permlane16_swap_b32_e32 v169, v179
	v_lshlrev_b32_e32 v166, 16, v164
	v_and_b32_e32 v167, 0xffff0000, v164
	v_lshlrev_b32_e32 v164, 16, v165
	v_and_b32_e32 v165, 0xffff0000, v165
	v_lshlrev_b32_e32 v170, 16, v172
	v_and_b32_e32 v171, 0xffff0000, v172
	v_lshlrev_b32_e32 v172, 16, v173
	v_and_b32_e32 v173, 0xffff0000, v173
	v_lshlrev_b32_e32 v174, 16, v168
	v_and_b32_e32 v175, 0xffff0000, v168
	v_lshlrev_b32_e32 v168, 16, v169
	v_and_b32_e32 v169, 0xffff0000, v169
	v_pk_fma_f32 v[126:127], v[126:127], v[106:107], v[164:165]
	v_pk_fma_f32 v[124:125], v[124:125], v[104:105], v[166:167]
	v_pk_fma_f32 v[122:123], v[122:123], v[110:111], v[172:173]
	v_pk_fma_f32 v[120:121], v[120:121], v[108:109], v[170:171]
	v_lshlrev_b32_e32 v176, 16, v177
	v_and_b32_e32 v177, 0xffff0000, v177
	v_lshlrev_b32_e32 v178, 16, v179
	v_and_b32_e32 v179, 0xffff0000, v179
	v_pk_fma_f32 v[118:119], v[118:119], v[102:103], v[168:169]
	v_pk_fma_f32 v[116:117], v[116:117], v[100:101], v[174:175]
	v_mul_f32_e32 v164, v125, v125
	v_mul_f32_e32 v165, v127, v127
	v_mul_f32_e32 v166, v121, v121
	v_mul_f32_e32 v167, v123, v123
	v_pk_fma_f32 v[114:115], v[114:115], v[98:99], v[178:179]
	v_pk_fma_f32 v[112:113], v[112:113], v[96:97], v[176:177]
	v_mul_f32_e32 v168, v117, v117
	v_mul_f32_e32 v169, v119, v119
	v_fmac_f32_e32 v164, v124, v124
	v_fmac_f32_e32 v165, v126, v126
	v_fmac_f32_e32 v166, v120, v120
	v_fmac_f32_e32 v167, v122, v122
	v_mul_f32_e32 v170, v113, v113
	v_mul_f32_e32 v171, v115, v115
	v_fmac_f32_e32 v168, v116, v116
	v_fmac_f32_e32 v169, v118, v118
	v_add_f32_e32 v164, v164, v165
	v_add_f32_e32 v165, v166, v167
	v_fmac_f32_e32 v170, v112, v112
	v_fmac_f32_e32 v171, v114, v114
	v_add_f32_e32 v166, v168, v169
	v_add_f32_e32 v164, v164, v165
	v_add_f32_e32 v164, v164, v166
	v_add_f32_e32 v165, v170, v171
	v_add_f32_e32 v164, v165, v164
	ds_bpermute_b32 v165, v191, v164
	s_waitcnt lgkmcnt(0)
	v_add_f32_e32 v164, v164, v165
	ds_bpermute_b32 v165, v192, v164
	s_and_saveexec_b64 s[4:5], s[0:1]
	s_cbranch_execz .LBB0_1466
	s_waitcnt lgkmcnt(0)
	v_add_f32_e32 v164, v164, v165
	ds_write_b32 v189, v164 offset:256
.LBB0_1466:
	s_or_b64 exec, exec, s[4:5]
	v_or_b32_e32 v164, 32, v160
	s_waitcnt lgkmcnt(0)
	v_ashrrev_i32_e32 v165, 31, v164
	v_lshlrev_b64 v[166:167], 11, v[164:165]
	v_lshl_add_u64 v[166:167], s[74:75], 0, v[166:167]
	v_lshl_add_u64 v[166:167], v[158:159], 1, v[166:167]
	v_lshl_add_u64 v[170:171], v[166:167], 0, v[148:149]
	s_waitcnt vmcnt(10)
	v_mov_b64_e32 v[166:167], v[236:237]
	v_mov_b64_e32 v[168:169], v[238:239]
	s_nop 0
	v_mov_b64_e32 v[170:171], v[240:241]
	v_mov_b64_e32 v[172:173], v[242:243]
	s_nop 0
	v_mov_b32_e32 v174, v168
	v_mov_b32_e32 v175, v169
	s_nop 0
	v_mov_b32_e32 v179, v172
	v_mov_b32_e32 v193, v173
	v_permlane16_swap_b32_e32 v166, v174
	v_permlane16_swap_b32_e32 v167, v175
	v_permlane16_swap_b32_e32 v170, v179
	v_permlane16_swap_b32_e32 v171, v193
	v_lshlrev_b32_e32 v168, 16, v166
	v_and_b32_e32 v169, 0xffff0000, v166
	v_lshlrev_b32_e32 v166, 16, v167
	v_and_b32_e32 v167, 0xffff0000, v167
	v_lshlrev_b32_e32 v172, 16, v174
	v_and_b32_e32 v173, 0xffff0000, v174
	v_lshlrev_b32_e32 v174, 16, v175
	v_and_b32_e32 v175, 0xffff0000, v175
	v_lshlrev_b32_e32 v176, 16, v170
	v_and_b32_e32 v177, 0xffff0000, v170
	v_lshlrev_b32_e32 v170, 16, v171
	v_and_b32_e32 v171, 0xffff0000, v171
	v_pk_fma_f32 v[94:95], v[94:95], v[106:107], v[166:167]
	v_pk_fma_f32 v[92:93], v[92:93], v[104:105], v[168:169]
	v_pk_fma_f32 v[90:91], v[90:91], v[110:111], v[174:175]
	v_pk_fma_f32 v[88:89], v[88:89], v[108:109], v[172:173]
	v_lshlrev_b32_e32 v178, 16, v179
	v_and_b32_e32 v179, 0xffff0000, v179
	v_lshlrev_b32_e32 v194, 16, v193
	v_and_b32_e32 v195, 0xffff0000, v193
	v_pk_fma_f32 v[86:87], v[86:87], v[102:103], v[170:171]
	v_pk_fma_f32 v[84:85], v[84:85], v[100:101], v[176:177]
	v_mul_f32_e32 v166, v93, v93
	v_mul_f32_e32 v167, v95, v95
	v_mul_f32_e32 v168, v89, v89
	v_mul_f32_e32 v169, v91, v91
	v_pk_fma_f32 v[82:83], v[82:83], v[98:99], v[194:195]
	v_pk_fma_f32 v[80:81], v[80:81], v[96:97], v[178:179]
	v_mul_f32_e32 v170, v85, v85
	v_mul_f32_e32 v171, v87, v87
	v_fmac_f32_e32 v166, v92, v92
	v_fmac_f32_e32 v167, v94, v94
	v_fmac_f32_e32 v168, v88, v88
	v_fmac_f32_e32 v169, v90, v90
	v_mul_f32_e32 v172, v81, v81
	v_mul_f32_e32 v173, v83, v83
	v_fmac_f32_e32 v170, v84, v84
	v_fmac_f32_e32 v171, v86, v86
	v_add_f32_e32 v166, v166, v167
	v_add_f32_e32 v167, v168, v169
	v_fmac_f32_e32 v172, v80, v80
	v_fmac_f32_e32 v173, v82, v82
	v_add_f32_e32 v168, v170, v171
	v_add_f32_e32 v166, v166, v167
	v_add_f32_e32 v166, v166, v168
	v_add_f32_e32 v167, v172, v173
	v_add_f32_e32 v166, v167, v166
	ds_bpermute_b32 v167, v191, v166
	s_waitcnt lgkmcnt(0)
	v_add_f32_e32 v166, v166, v167
	ds_bpermute_b32 v167, v192, v166
	s_and_saveexec_b64 s[4:5], s[0:1]
	s_cbranch_execz .LBB0_1468
	s_waitcnt lgkmcnt(0)
	v_add_f32_e32 v166, v166, v167
	ds_write_b32 v189, v166 offset:512
.LBB0_1468:
	s_or_b64 exec, exec, s[4:5]
	v_or_b32_e32 v166, 48, v160
	s_waitcnt lgkmcnt(0)
	v_ashrrev_i32_e32 v167, 31, v166
	v_lshlrev_b64 v[168:169], 11, v[166:167]
	v_lshl_add_u64 v[168:169], s[74:75], 0, v[168:169]
	v_lshl_add_u64 v[168:169], v[158:159], 1, v[168:169]
	v_lshl_add_u64 v[172:173], v[168:169], 0, v[148:149]
	s_waitcnt vmcnt(8)
	v_mov_b64_e32 v[168:169], v[244:245]
	v_mov_b64_e32 v[170:171], v[246:247]
	s_nop 0
	v_mov_b64_e32 v[172:173], v[248:249]
	v_mov_b64_e32 v[174:175], v[250:251]
	s_nop 0
	v_mov_b32_e32 v176, v170
	v_mov_b32_e32 v177, v171
	s_nop 0
	v_mov_b32_e32 v193, v174
	v_mov_b32_e32 v197, v175
	v_permlane16_swap_b32_e32 v168, v176
	v_permlane16_swap_b32_e32 v169, v177
	v_permlane16_swap_b32_e32 v172, v193
	v_permlane16_swap_b32_e32 v173, v197
	v_lshlrev_b32_e32 v170, 16, v168
	v_and_b32_e32 v171, 0xffff0000, v168
	v_lshlrev_b32_e32 v168, 16, v169
	v_and_b32_e32 v169, 0xffff0000, v169
	v_lshlrev_b32_e32 v174, 16, v176
	v_and_b32_e32 v175, 0xffff0000, v176
	v_lshlrev_b32_e32 v176, 16, v177
	v_and_b32_e32 v177, 0xffff0000, v177
	v_lshlrev_b32_e32 v178, 16, v172
	v_and_b32_e32 v179, 0xffff0000, v172
	v_lshlrev_b32_e32 v172, 16, v173
	v_and_b32_e32 v173, 0xffff0000, v173
	v_pk_fma_f32 v[168:169], v[78:79], v[106:107], v[168:169]
	v_pk_fma_f32 v[76:77], v[76:77], v[104:105], v[170:171]
	v_pk_fma_f32 v[74:75], v[74:75], v[110:111], v[176:177]
	v_pk_fma_f32 v[72:73], v[72:73], v[108:109], v[174:175]
	v_lshlrev_b32_e32 v194, 16, v193
	v_and_b32_e32 v195, 0xffff0000, v193
	v_lshlrev_b32_e32 v196, 16, v197
	v_and_b32_e32 v197, 0xffff0000, v197
	v_pk_fma_f32 v[70:71], v[70:71], v[102:103], v[172:173]
	v_pk_fma_f32 v[68:69], v[68:69], v[100:101], v[178:179]
	v_mul_f32_e32 v78, v77, v77
	v_mul_f32_e32 v79, v169, v169
	v_mul_f32_e32 v170, v73, v73
	v_mul_f32_e32 v171, v75, v75
	v_pk_fma_f32 v[66:67], v[66:67], v[98:99], v[196:197]
	v_pk_fma_f32 v[64:65], v[64:65], v[96:97], v[194:195]
	v_mul_f32_e32 v172, v69, v69
	v_mul_f32_e32 v173, v71, v71
	v_fmac_f32_e32 v78, v76, v76
	v_fmac_f32_e32 v79, v168, v168
	v_fmac_f32_e32 v170, v72, v72
	v_fmac_f32_e32 v171, v74, v74
	v_mul_f32_e32 v174, v65, v65
	v_mul_f32_e32 v175, v67, v67
	v_fmac_f32_e32 v172, v68, v68
	v_fmac_f32_e32 v173, v70, v70
	v_add_f32_e32 v78, v78, v79
	v_add_f32_e32 v79, v170, v171
	v_fmac_f32_e32 v174, v64, v64
	v_fmac_f32_e32 v175, v66, v66
	v_add_f32_e32 v170, v172, v173
	v_add_f32_e32 v78, v78, v79
	v_add_f32_e32 v78, v78, v170
	v_add_f32_e32 v79, v174, v175
	v_add_f32_e32 v78, v79, v78
	ds_bpermute_b32 v79, v191, v78
	s_waitcnt lgkmcnt(0)
	v_add_f32_e32 v78, v78, v79
	ds_bpermute_b32 v79, v192, v78
	s_and_saveexec_b64 s[4:5], s[0:1]
	s_cbranch_execz .LBB0_1470
	s_waitcnt lgkmcnt(0)
	v_add_f32_e32 v78, v78, v79
	ds_write_b32 v189, v78 offset:768
.LBB0_1470:
	s_or_b64 exec, exec, s[4:5]
	v_add_u32_e32 v78, 0x80, v160
	s_waitcnt lgkmcnt(0)
	v_ashrrev_i32_e32 v79, 31, v78
	v_lshlrev_b64 v[170:171], 11, v[78:79]
	v_lshl_add_u64 v[170:171], s[74:75], 0, v[170:171]
	v_lshl_add_u64 v[170:171], v[158:159], 1, v[170:171]
	v_lshl_add_u64 v[174:175], v[170:171], 0, v[148:149]
	s_waitcnt vmcnt(6)
	v_mov_b64_e32 v[170:171], v[252:253]
	v_mov_b64_e32 v[172:173], v[254:255]
	s_nop 0
	v_mov_b64_e32 v[174:175], v[144:145]
	v_mov_b64_e32 v[176:177], v[146:147]
	s_nop 0
	v_mov_b32_e32 v178, v172
	v_mov_b32_e32 v179, v173
	s_nop 0
	v_mov_b32_e32 v193, v176
	v_mov_b32_e32 v199, v177
	v_permlane16_swap_b32_e32 v170, v178
	v_permlane16_swap_b32_e32 v171, v179
	v_permlane16_swap_b32_e32 v174, v193
	v_permlane16_swap_b32_e32 v175, v199
	v_lshlrev_b32_e32 v172, 16, v170
	v_and_b32_e32 v173, 0xffff0000, v170
	v_lshlrev_b32_e32 v170, 16, v171
	v_and_b32_e32 v171, 0xffff0000, v171
	v_lshlrev_b32_e32 v176, 16, v178
	v_and_b32_e32 v177, 0xffff0000, v178
	v_lshlrev_b32_e32 v178, 16, v179
	v_and_b32_e32 v179, 0xffff0000, v179
	v_lshlrev_b32_e32 v194, 16, v174
	v_and_b32_e32 v195, 0xffff0000, v174
	v_lshlrev_b32_e32 v174, 16, v175
	v_and_b32_e32 v175, 0xffff0000, v175
	v_pk_fma_f32 v[62:63], v[62:63], v[106:107], v[170:171]
	v_pk_fma_f32 v[60:61], v[60:61], v[104:105], v[172:173]
	v_pk_fma_f32 v[58:59], v[58:59], v[110:111], v[178:179]
	v_pk_fma_f32 v[56:57], v[56:57], v[108:109], v[176:177]
	v_lshlrev_b32_e32 v196, 16, v193
	v_and_b32_e32 v197, 0xffff0000, v193
	v_lshlrev_b32_e32 v198, 16, v199
	v_and_b32_e32 v199, 0xffff0000, v199
	v_pk_fma_f32 v[54:55], v[54:55], v[102:103], v[174:175]
	v_pk_fma_f32 v[52:53], v[52:53], v[100:101], v[194:195]
	v_mul_f32_e32 v170, v61, v61
	v_mul_f32_e32 v171, v63, v63
	v_mul_f32_e32 v172, v57, v57
	v_mul_f32_e32 v173, v59, v59
	v_pk_fma_f32 v[50:51], v[50:51], v[98:99], v[198:199]
	v_pk_fma_f32 v[48:49], v[48:49], v[96:97], v[196:197]
	v_mul_f32_e32 v174, v53, v53
	v_mul_f32_e32 v175, v55, v55
	v_fmac_f32_e32 v170, v60, v60
	v_fmac_f32_e32 v171, v62, v62
	v_fmac_f32_e32 v172, v56, v56
	v_fmac_f32_e32 v173, v58, v58
	v_mul_f32_e32 v176, v49, v49
	v_mul_f32_e32 v177, v51, v51
	v_fmac_f32_e32 v174, v52, v52
	v_fmac_f32_e32 v175, v54, v54
	v_add_f32_e32 v170, v170, v171
	v_add_f32_e32 v171, v172, v173
	v_fmac_f32_e32 v176, v48, v48
	v_fmac_f32_e32 v177, v50, v50
	v_add_f32_e32 v172, v174, v175
	v_add_f32_e32 v170, v170, v171
	v_add_f32_e32 v170, v170, v172
	v_add_f32_e32 v171, v176, v177
	v_add_f32_e32 v170, v171, v170
	ds_bpermute_b32 v171, v191, v170
	s_waitcnt lgkmcnt(0)
	v_add_f32_e32 v170, v170, v171
	ds_bpermute_b32 v171, v192, v170
	s_and_saveexec_b64 s[4:5], s[0:1]
	s_cbranch_execz .LBB0_1472
	s_waitcnt lgkmcnt(0)
	v_add_f32_e32 v170, v170, v171
	ds_write_b32 v189, v170 offset:2048
.LBB0_1472:
	s_or_b64 exec, exec, s[4:5]
	v_add_u32_e32 v170, 0x90, v160
	s_waitcnt lgkmcnt(0)
	v_ashrrev_i32_e32 v171, 31, v170
	v_lshlrev_b64 v[172:173], 11, v[170:171]
	v_lshl_add_u64 v[172:173], s[74:75], 0, v[172:173]
	v_lshl_add_u64 v[172:173], v[158:159], 1, v[172:173]
	v_lshl_add_u64 v[176:177], v[172:173], 0, v[148:149]
	s_waitcnt vmcnt(4)
	v_mov_b64_e32 v[172:173], v[150:151]
	v_mov_b64_e32 v[174:175], v[152:153]
	s_nop 0
	v_mov_b64_e32 v[176:177], v[154:155]
	v_mov_b64_e32 v[178:179], v[156:157]
	s_nop 0
	v_mov_b32_e32 v193, v174
	v_mov_b32_e32 v195, v175
	s_nop 0
	v_mov_b32_e32 v199, v178
	v_mov_b32_e32 v201, v179
	v_permlane16_swap_b32_e32 v172, v193
	v_permlane16_swap_b32_e32 v173, v195
	v_permlane16_swap_b32_e32 v176, v199
	v_permlane16_swap_b32_e32 v177, v201
	v_lshlrev_b32_e32 v174, 16, v172
	v_and_b32_e32 v175, 0xffff0000, v172
	v_lshlrev_b32_e32 v172, 16, v173
	v_and_b32_e32 v173, 0xffff0000, v173
	v_lshlrev_b32_e32 v178, 16, v193
	v_and_b32_e32 v179, 0xffff0000, v193
	v_lshlrev_b32_e32 v194, 16, v195
	v_and_b32_e32 v195, 0xffff0000, v195
	v_lshlrev_b32_e32 v196, 16, v176
	v_and_b32_e32 v197, 0xffff0000, v176
	v_lshlrev_b32_e32 v176, 16, v177
	v_and_b32_e32 v177, 0xffff0000, v177
	v_pk_fma_f32 v[46:47], v[46:47], v[106:107], v[172:173]
	v_pk_fma_f32 v[44:45], v[44:45], v[104:105], v[174:175]
	v_pk_fma_f32 v[42:43], v[42:43], v[110:111], v[194:195]
	v_pk_fma_f32 v[40:41], v[40:41], v[108:109], v[178:179]
	v_lshlrev_b32_e32 v198, 16, v199
	v_and_b32_e32 v199, 0xffff0000, v199
	v_lshlrev_b32_e32 v200, 16, v201
	v_and_b32_e32 v201, 0xffff0000, v201
	v_pk_fma_f32 v[38:39], v[38:39], v[102:103], v[176:177]
	v_pk_fma_f32 v[36:37], v[36:37], v[100:101], v[196:197]
	v_mul_f32_e32 v172, v45, v45
	v_mul_f32_e32 v173, v47, v47
	v_mul_f32_e32 v174, v41, v41
	v_mul_f32_e32 v175, v43, v43
	v_pk_fma_f32 v[34:35], v[34:35], v[98:99], v[200:201]
	v_pk_fma_f32 v[32:33], v[32:33], v[96:97], v[198:199]
	v_mul_f32_e32 v176, v37, v37
	v_mul_f32_e32 v177, v39, v39
	v_fmac_f32_e32 v172, v44, v44
	v_fmac_f32_e32 v173, v46, v46
	v_fmac_f32_e32 v174, v40, v40
	v_fmac_f32_e32 v175, v42, v42
	v_mul_f32_e32 v178, v33, v33
	v_mul_f32_e32 v179, v35, v35
	v_fmac_f32_e32 v176, v36, v36
	v_fmac_f32_e32 v177, v38, v38
	v_add_f32_e32 v172, v172, v173
	v_add_f32_e32 v173, v174, v175
	v_fmac_f32_e32 v178, v32, v32
	v_fmac_f32_e32 v179, v34, v34
	v_add_f32_e32 v174, v176, v177
	v_add_f32_e32 v172, v172, v173
	v_add_f32_e32 v172, v172, v174
	v_add_f32_e32 v173, v178, v179
	v_add_f32_e32 v172, v173, v172
	ds_bpermute_b32 v173, v191, v172
	s_waitcnt lgkmcnt(0)
	v_add_f32_e32 v172, v172, v173
	ds_bpermute_b32 v173, v192, v172
	s_and_saveexec_b64 s[4:5], s[0:1]
	s_cbranch_execz .LBB0_1474
	s_waitcnt lgkmcnt(0)
	v_add_f32_e32 v172, v172, v173
	ds_write_b32 v189, v172 offset:2304
.LBB0_1474:
	s_or_b64 exec, exec, s[4:5]
	v_add_u32_e32 v172, 0xa0, v160
	s_waitcnt lgkmcnt(0)
	v_ashrrev_i32_e32 v173, 31, v172
	v_lshlrev_b64 v[174:175], 11, v[172:173]
	v_lshl_add_u64 v[174:175], s[74:75], 0, v[174:175]
	v_lshl_add_u64 v[174:175], v[158:159], 1, v[174:175]
	v_lshl_add_u64 v[178:179], v[174:175], 0, v[148:149]
	s_waitcnt vmcnt(2)
	v_mov_b64_e32 v[174:175], v[210:211]
	v_mov_b64_e32 v[176:177], v[212:213]
	v_mov_b64_e32 v[194:195], v[214:215]
	v_mov_b64_e32 v[196:197], v[216:217]
	s_nop 0
	v_mov_b32_e32 v179, v176
	v_mov_b32_e32 v193, v177
	s_nop 0
	v_mov_b32_e32 v201, v196
	v_mov_b32_e32 v203, v197
	v_permlane16_swap_b32_e32 v174, v179
	v_permlane16_swap_b32_e32 v175, v193
	v_permlane16_swap_b32_e32 v194, v201
	v_permlane16_swap_b32_e32 v195, v203
	v_lshlrev_b32_e32 v176, 16, v174
	v_and_b32_e32 v177, 0xffff0000, v174
	v_lshlrev_b32_e32 v174, 16, v175
	v_and_b32_e32 v175, 0xffff0000, v175
	v_lshlrev_b32_e32 v178, 16, v179
	v_and_b32_e32 v179, 0xffff0000, v179
	v_lshlrev_b32_e32 v196, 16, v193
	v_and_b32_e32 v197, 0xffff0000, v193
	v_lshlrev_b32_e32 v198, 16, v194
	v_and_b32_e32 v199, 0xffff0000, v194
	v_lshlrev_b32_e32 v194, 16, v195
	v_and_b32_e32 v195, 0xffff0000, v195
	v_pk_fma_f32 v[30:31], v[30:31], v[106:107], v[174:175]
	v_pk_fma_f32 v[28:29], v[28:29], v[104:105], v[176:177]
	v_pk_fma_f32 v[26:27], v[26:27], v[110:111], v[196:197]
	v_pk_fma_f32 v[24:25], v[24:25], v[108:109], v[178:179]
	v_lshlrev_b32_e32 v200, 16, v201
	v_and_b32_e32 v201, 0xffff0000, v201
	v_lshlrev_b32_e32 v202, 16, v203
	v_and_b32_e32 v203, 0xffff0000, v203
	v_pk_fma_f32 v[22:23], v[22:23], v[102:103], v[194:195]
	v_pk_fma_f32 v[20:21], v[20:21], v[100:101], v[198:199]
	v_mul_f32_e32 v174, v29, v29
	v_mul_f32_e32 v175, v31, v31
	v_mul_f32_e32 v176, v25, v25
	v_mul_f32_e32 v177, v27, v27
	v_pk_fma_f32 v[18:19], v[18:19], v[98:99], v[202:203]
	v_pk_fma_f32 v[16:17], v[16:17], v[96:97], v[200:201]
	v_mul_f32_e32 v178, v21, v21
	v_mul_f32_e32 v179, v23, v23
	v_fmac_f32_e32 v174, v28, v28
	v_fmac_f32_e32 v175, v30, v30
	v_fmac_f32_e32 v176, v24, v24
	v_fmac_f32_e32 v177, v26, v26
	v_mul_f32_e32 v193, v17, v17
	v_mul_f32_e32 v194, v19, v19
	v_fmac_f32_e32 v178, v20, v20
	v_fmac_f32_e32 v179, v22, v22
	v_add_f32_e32 v174, v174, v175
	v_add_f32_e32 v175, v176, v177
	v_fmac_f32_e32 v193, v16, v16
	v_fmac_f32_e32 v194, v18, v18
	v_add_f32_e32 v176, v178, v179
	v_add_f32_e32 v174, v174, v175
	v_add_f32_e32 v174, v174, v176
	v_add_f32_e32 v175, v193, v194
	v_add_f32_e32 v174, v175, v174
	ds_bpermute_b32 v175, v191, v174
	s_waitcnt lgkmcnt(0)
	v_add_f32_e32 v174, v174, v175
	ds_bpermute_b32 v175, v192, v174
	s_and_saveexec_b64 s[4:5], s[0:1]
	s_cbranch_execz .LBB0_1476
	s_waitcnt lgkmcnt(0)
	v_add_f32_e32 v174, v174, v175
	ds_write_b32 v189, v174 offset:2560
.LBB0_1476:
	s_or_b64 exec, exec, s[4:5]
	v_add_u32_e32 v174, 0xb0, v160
	s_waitcnt lgkmcnt(0)
	v_ashrrev_i32_e32 v175, 31, v174
	v_lshlrev_b64 v[176:177], 11, v[174:175]
	v_lshl_add_u64 v[176:177], s[74:75], 0, v[176:177]
	v_lshl_add_u64 v[176:177], v[158:159], 1, v[176:177]
	v_lshl_add_u64 v[194:195], v[176:177], 0, v[148:149]
	s_waitcnt vmcnt(0)
	v_mov_b64_e32 v[176:177], v[220:221]
	v_mov_b64_e32 v[178:179], v[222:223]
	s_nop 0
	v_mov_b64_e32 v[194:195], v[224:225]
	v_mov_b64_e32 v[196:197], v[226:227]
	s_nop 0
	v_mov_b32_e32 v193, v178
	v_mov_b32_e32 v199, v179
	s_nop 0
	v_mov_b32_e32 v203, v196
	v_mov_b32_e32 v205, v197
	v_permlane16_swap_b32_e32 v176, v193
	v_permlane16_swap_b32_e32 v177, v199
	v_permlane16_swap_b32_e32 v194, v203
	v_permlane16_swap_b32_e32 v195, v205
	v_lshlrev_b32_e32 v178, 16, v176
	v_and_b32_e32 v179, 0xffff0000, v176
	v_lshlrev_b32_e32 v176, 16, v177
	v_and_b32_e32 v177, 0xffff0000, v177
	v_lshlrev_b32_e32 v196, 16, v193
	v_and_b32_e32 v197, 0xffff0000, v193
	v_lshlrev_b32_e32 v198, 16, v199
	v_and_b32_e32 v199, 0xffff0000, v199
	v_lshlrev_b32_e32 v200, 16, v194
	v_and_b32_e32 v201, 0xffff0000, v194
	v_lshlrev_b32_e32 v194, 16, v195
	v_and_b32_e32 v195, 0xffff0000, v195
	v_lshlrev_b32_e32 v202, 16, v203
	v_and_b32_e32 v203, 0xffff0000, v203
	v_lshlrev_b32_e32 v204, 16, v205
	v_and_b32_e32 v205, 0xffff0000, v205
	v_pk_fma_f32 v[176:177], v[14:15], v[106:107], v[176:177]
	v_pk_fma_f32 v[178:179], v[12:13], v[104:105], v[178:179]
	v_pk_fma_f32 v[104:105], v[10:11], v[110:111], v[198:199]
	v_pk_fma_f32 v[106:107], v[8:9], v[108:109], v[196:197]
	v_pk_fma_f32 v[102:103], v[6:7], v[102:103], v[194:195]
	v_pk_fma_f32 v[100:101], v[4:5], v[100:101], v[200:201]
	v_pk_fma_f32 v[98:99], v[2:3], v[98:99], v[204:205]
	v_pk_fma_f32 v[96:97], v[0:1], v[96:97], v[202:203]
	v_mul_f32_e32 v0, v179, v179
	v_mul_f32_e32 v1, v177, v177
	v_mul_f32_e32 v2, v107, v107
	v_mul_f32_e32 v3, v105, v105
	v_mul_f32_e32 v4, v101, v101
	v_mul_f32_e32 v5, v103, v103
	v_fmac_f32_e32 v0, v178, v178
	v_fmac_f32_e32 v1, v176, v176
	v_fmac_f32_e32 v2, v106, v106
	v_fmac_f32_e32 v3, v104, v104
	v_mul_f32_e32 v6, v97, v97
	v_mul_f32_e32 v7, v99, v99
	v_fmac_f32_e32 v4, v100, v100
	v_fmac_f32_e32 v5, v102, v102
	v_add_f32_e32 v0, v0, v1
	v_add_f32_e32 v1, v2, v3
	v_fmac_f32_e32 v6, v96, v96
	v_fmac_f32_e32 v7, v98, v98
	v_add_f32_e32 v2, v4, v5
	v_add_f32_e32 v0, v0, v1
	v_add_f32_e32 v0, v0, v2
	v_add_f32_e32 v1, v6, v7
	v_add_f32_e32 v0, v1, v0
	ds_bpermute_b32 v1, v191, v0
	s_waitcnt lgkmcnt(0)
	v_add_f32_e32 v0, v0, v1
	ds_bpermute_b32 v1, v192, v0
	s_and_saveexec_b64 s[4:5], s[0:1]
	s_cbranch_execz .LBB0_1478
	s_waitcnt lgkmcnt(0)
	v_add_f32_e32 v0, v0, v1
	ds_write_b32 v189, v0 offset:2816

	.amdhsa_kernel _Z14fwd_megakernel4Args
		.amdhsa_group_segment_fixed_size 0
		.amdhsa_private_segment_fixed_size 0
		.amdhsa_kernarg_size 472
		.amdhsa_user_sgpr_count 2
		.amdhsa_user_sgpr_dispatch_ptr 0
		.amdhsa_user_sgpr_queue_ptr 0
		.amdhsa_user_sgpr_kernarg_segment_ptr 1
		.amdhsa_user_sgpr_dispatch_id 0
		.amdhsa_user_sgpr_kernarg_preload_length 0
		.amdhsa_user_sgpr_kernarg_preload_offset 0
		.amdhsa_user_sgpr_private_segment_size 0
		.amdhsa_uses_dynamic_stack 0
		.amdhsa_enable_private_segment 0
		.amdhsa_system_sgpr_workgroup_id_x 1
		.amdhsa_system_sgpr_workgroup_id_y 0
		.amdhsa_system_sgpr_workgroup_id_z 0
		.amdhsa_system_sgpr_workgroup_info 0
		.amdhsa_system_vgpr_workitem_id 2
		.amdhsa_next_free_vgpr 256
		.amdhsa_next_free_sgpr 98
		.amdhsa_accum_offset 256
		.amdhsa_reserve_vcc 1
		.amdhsa_float_round_mode_32 0
		.amdhsa_float_round_mode_16_64 0
		.amdhsa_float_denorm_mode_32 3
		.amdhsa_float_denorm_mode_16_64 3
		.amdhsa_dx10_clamp 1
		.amdhsa_ieee_mode 1
		.amdhsa_fp16_overflow 0
		.amdhsa_tg_split 0
		.amdhsa_exception_fp_ieee_invalid_op 0
		.amdhsa_exception_fp_denorm_src 0
		.amdhsa_exception_fp_ieee_div_zero 0
		.amdhsa_exception_fp_ieee_overflow 0
		.amdhsa_exception_fp_ieee_underflow 0
		.amdhsa_exception_fp_ieee_inexact 0
		.amdhsa_exception_int_div_zero 0
	.end_amdhsa_kernel

amdhsa.kernels:
  - .agpr_count:     0
    .args:
      - .offset:         0
        .size:           216
        .value_kind:     by_value
      - .offset:         216
        .size:           4
        .value_kind:     hidden_block_count_x
      - .offset:         220
        .size:           4
        .value_kind:     hidden_block_count_y
      - .offset:         224
        .size:           4
        .value_kind:     hidden_block_count_z
      - .offset:         228
        .size:           2
        .value_kind:     hidden_group_size_x
      - .offset:         230
        .size:           2
        .value_kind:     hidden_group_size_y
      - .offset:         232
        .size:           2
        .value_kind:     hidden_group_size_z
      - .offset:         234
        .size:           2
        .value_kind:     hidden_remainder_x
      - .offset:         236
        .size:           2
        .value_kind:     hidden_remainder_y
      - .offset:         238
        .size:           2
        .value_kind:     hidden_remainder_z
      - .offset:         256
        .size:           8
        .value_kind:     hidden_global_offset_x
      - .offset:         264
        .size:           8
        .value_kind:     hidden_global_offset_y
      - .offset:         272
        .size:           8
        .value_kind:     hidden_global_offset_z
      - .offset:         280
        .size:           2
        .value_kind:     hidden_grid_dims
      - .offset:         304
        .size:           8
        .value_kind:     hidden_multigrid_sync_arg
      - .offset:         336
        .size:           4
        .value_kind:     hidden_dynamic_lds_size
    .group_segment_fixed_size: 0
    .kernarg_segment_align: 8
    .kernarg_segment_size: 472
    .language:       OpenCL C
    .language_version:
      - 2
      - 0
    .max_flat_workgroup_size: 512
    .name:           _Z14fwd_megakernel4Args
    .private_segment_fixed_size: 0
    .sgpr_count:     104
    .sgpr_spill_count: 95
    .symbol:         _Z14fwd_megakernel4Args.kd
    .uniform_work_group_size: 1
    .uses_dynamic_stack: false
    .vgpr_count:     256
    .vgpr_spill_count: 0
    .wavefront_size: 64
